# P1 hand-written only (without the P9 rewrite)
# speedup vs baseline: 1.0072x; 1.0072x over previous
.LBB0_112:
	s_cmp_lt_i32 s78, 2
	s_cselect_b64 s[8:9], -1, 0
	s_and_b64 s[2:3], s[8:9], s[2:3]
	s_andn2_b64 vcc, exec, s[2:3]
	s_cbranch_vccnz .LBB0_122
	s_cmpk_lg_i32 s92, 0x100
	s_cbranch_scc1 .Lp1_generic
	v_readfirstlane_b32 s9, v243
	s_lshl_b32 s8, s96, 3
	s_lshr_b32 s9, s9, 6
	s_add_i32 s8, s9, s8
	v_lshlrev_b32_e32 v232, 4, v242
	v_add_u32_e32 v233, 0x1000, v232
	v_lshlrev_b32_e32 v234, 3, v242
	v_mov_b32_e32 v235, 0x358637bd
	v_xor_b32_e32 v224, 1, v242
	v_lshlrev_b32_e32 v224, 2, v224
	v_xor_b32_e32 v225, 2, v242
	v_lshlrev_b32_e32 v225, 2, v225
	v_xor_b32_e32 v226, 4, v242
	v_lshlrev_b32_e32 v226, 2, v226
	v_xor_b32_e32 v227, 8, v242
	v_lshlrev_b32_e32 v227, 2, v227
	v_xor_b32_e32 v228, 16, v242
	v_lshlrev_b32_e32 v228, 2, v228
	v_xor_b32_e32 v229, 32, v242
	v_lshlrev_b32_e32 v229, 2, v229
	s_add_u32 s24, s76, 0x2000
	s_addc_u32 s25, s77, 0
	global_load_dwordx4 v[128:131], v232, s[4:5] offset:0
	global_load_dwordx4 v[132:135], v232, s[4:5] offset:1024
	global_load_dwordx4 v[136:139], v232, s[4:5] offset:2048
	global_load_dwordx4 v[140:143], v232, s[4:5] offset:3072
	global_load_dwordx4 v[144:147], v233, s[4:5] offset:0
	global_load_dwordx4 v[148:151], v233, s[4:5] offset:1024
	global_load_dwordx4 v[152:155], v233, s[4:5] offset:2048
	global_load_dwordx4 v[156:159], v233, s[4:5] offset:3072
	global_load_dwordx4 v[160:163], v232, s[24:25] offset:0
	global_load_dwordx4 v[164:167], v232, s[24:25] offset:1024
	global_load_dwordx4 v[168:171], v232, s[24:25] offset:2048
	global_load_dwordx4 v[172:175], v232, s[24:25] offset:3072
	global_load_dwordx4 v[176:179], v233, s[24:25] offset:0
	global_load_dwordx4 v[180:183], v233, s[24:25] offset:1024
	global_load_dwordx4 v[184:187], v233, s[24:25] offset:2048
	global_load_dwordx4 v[188:191], v233, s[24:25] offset:3072
	global_load_dwordx4 v[192:195], v232, s[76:77] offset:0
	global_load_dwordx4 v[196:199], v232, s[76:77] offset:1024
	global_load_dwordx4 v[200:203], v232, s[76:77] offset:2048
	global_load_dwordx4 v[204:207], v232, s[76:77] offset:3072
	global_load_dwordx4 v[208:211], v233, s[76:77] offset:0
	global_load_dwordx4 v[212:215], v233, s[76:77] offset:1024
	global_load_dwordx4 v[216:219], v233, s[76:77] offset:2048
	global_load_dwordx4 v[220:223], v233, s[76:77] offset:3072
	s_mov_b32 s28, s8
	s_lshl_b32 s28, s28, 13
	s_add_u32 s20, s56, s28
	s_addc_u32 s21, s57, 0
	global_load_dwordx4 v[0:3], v232, s[20:21] offset:0 nt
	global_load_dwordx4 v[4:7], v232, s[20:21] offset:1024 nt
	global_load_dwordx4 v[8:11], v232, s[20:21] offset:2048 nt
	global_load_dwordx4 v[12:15], v232, s[20:21] offset:3072 nt
	global_load_dwordx4 v[16:19], v233, s[20:21] offset:0 nt
	global_load_dwordx4 v[20:23], v233, s[20:21] offset:1024 nt
	global_load_dwordx4 v[24:27], v233, s[20:21] offset:2048 nt
	global_load_dwordx4 v[28:31], v233, s[20:21] offset:3072 nt
	s_add_i32 s28, s8, 0x800
	s_lshl_b32 s28, s28, 13
	s_add_u32 s20, s56, s28
	s_addc_u32 s21, s57, 0
	global_load_dwordx4 v[32:35], v232, s[20:21] offset:0 nt
	global_load_dwordx4 v[36:39], v232, s[20:21] offset:1024 nt
	global_load_dwordx4 v[40:43], v232, s[20:21] offset:2048 nt
	global_load_dwordx4 v[44:47], v232, s[20:21] offset:3072 nt
	global_load_dwordx4 v[48:51], v233, s[20:21] offset:0 nt
	global_load_dwordx4 v[52:55], v233, s[20:21] offset:1024 nt
	global_load_dwordx4 v[56:59], v233, s[20:21] offset:2048 nt
	global_load_dwordx4 v[60:63], v233, s[20:21] offset:3072 nt
	s_add_i32 s28, s8, 0x1000
	s_lshl_b32 s28, s28, 13
	s_add_u32 s20, s56, s28
	s_addc_u32 s21, s57, 0
	global_load_dwordx4 v[64:67], v232, s[20:21] offset:0 nt
	global_load_dwordx4 v[68:71], v232, s[20:21] offset:1024 nt
	global_load_dwordx4 v[72:75], v232, s[20:21] offset:2048 nt
	global_load_dwordx4 v[76:79], v232, s[20:21] offset:3072 nt
	global_load_dwordx4 v[80:83], v233, s[20:21] offset:0 nt
	global_load_dwordx4 v[84:87], v233, s[20:21] offset:1024 nt
	global_load_dwordx4 v[88:91], v233, s[20:21] offset:2048 nt
	global_load_dwordx4 v[92:95], v233, s[20:21] offset:3072 nt
	s_waitcnt vmcnt(24)
	v_pk_add_f32 v[160:161], v[160:161], 1.0 op_sel_hi:[1,0]
	v_pk_add_f32 v[162:163], v[162:163], 1.0 op_sel_hi:[1,0]
	v_pk_add_f32 v[164:165], v[164:165], 1.0 op_sel_hi:[1,0]
	v_pk_add_f32 v[166:167], v[166:167], 1.0 op_sel_hi:[1,0]
	v_pk_add_f32 v[168:169], v[168:169], 1.0 op_sel_hi:[1,0]
	v_pk_add_f32 v[170:171], v[170:171], 1.0 op_sel_hi:[1,0]
	v_pk_add_f32 v[172:173], v[172:173], 1.0 op_sel_hi:[1,0]
	v_pk_add_f32 v[174:175], v[174:175], 1.0 op_sel_hi:[1,0]
	v_pk_add_f32 v[176:177], v[176:177], 1.0 op_sel_hi:[1,0]
	v_pk_add_f32 v[178:179], v[178:179], 1.0 op_sel_hi:[1,0]
	v_pk_add_f32 v[180:181], v[180:181], 1.0 op_sel_hi:[1,0]
	v_pk_add_f32 v[182:183], v[182:183], 1.0 op_sel_hi:[1,0]
	v_pk_add_f32 v[184:185], v[184:185], 1.0 op_sel_hi:[1,0]
	v_pk_add_f32 v[186:187], v[186:187], 1.0 op_sel_hi:[1,0]
	v_pk_add_f32 v[188:189], v[188:189], 1.0 op_sel_hi:[1,0]
	v_pk_add_f32 v[190:191], v[190:191], 1.0 op_sel_hi:[1,0]
	s_waitcnt vmcnt(16)
	v_pk_mul_f32 v[236:237], v[0:1], v[0:1]
	v_pk_fma_f32 v[236:237], v[2:3], v[2:3], v[236:237]
	v_pk_fma_f32 v[236:237], v[4:5], v[4:5], v[236:237]
	v_pk_fma_f32 v[236:237], v[6:7], v[6:7], v[236:237]
	v_pk_fma_f32 v[236:237], v[8:9], v[8:9], v[236:237]
	v_pk_fma_f32 v[236:237], v[10:11], v[10:11], v[236:237]
	v_pk_fma_f32 v[236:237], v[12:13], v[12:13], v[236:237]
	v_pk_fma_f32 v[236:237], v[14:15], v[14:15], v[236:237]
	v_pk_fma_f32 v[236:237], v[16:17], v[16:17], v[236:237]
	v_pk_fma_f32 v[236:237], v[18:19], v[18:19], v[236:237]
	v_pk_fma_f32 v[236:237], v[20:21], v[20:21], v[236:237]
	v_pk_fma_f32 v[236:237], v[22:23], v[22:23], v[236:237]
	v_pk_fma_f32 v[236:237], v[24:25], v[24:25], v[236:237]
	v_pk_fma_f32 v[236:237], v[26:27], v[26:27], v[236:237]
	v_pk_fma_f32 v[236:237], v[28:29], v[28:29], v[236:237]
	v_pk_fma_f32 v[236:237], v[30:31], v[30:31], v[236:237]
	v_add_f32_e32 v236, v236, v237
	ds_bpermute_b32 v237, v224, v236
	s_waitcnt lgkmcnt(0)
	v_add_f32_e32 v236, v236, v237
	ds_bpermute_b32 v237, v225, v236
	s_waitcnt lgkmcnt(0)
	v_add_f32_e32 v236, v236, v237
	ds_bpermute_b32 v237, v226, v236
	s_waitcnt lgkmcnt(0)
	v_add_f32_e32 v236, v236, v237
	ds_bpermute_b32 v237, v227, v236
	s_waitcnt lgkmcnt(0)
	v_add_f32_e32 v236, v236, v237
	ds_bpermute_b32 v237, v228, v236
	s_waitcnt lgkmcnt(0)
	v_add_f32_e32 v236, v236, v237
	ds_bpermute_b32 v237, v229, v236
	s_waitcnt lgkmcnt(0)
	v_add_f32_e32 v236, v236, v237
	v_fmamk_f32 v236, v236, 0x3a000000, v235
	v_rsq_f32_e32 v236, v236
	s_mov_b32 s28, s8
	s_lshl_b32 s28, s28, 12
	s_add_u32 s22, s76, s28
	s_addc_u32 s23, s77, 0
	s_add_u32 s22, s22, 0x7600000
	s_addc_u32 s23, s23, 0
	v_pk_mul_f32 v[0:1], v[0:1], v[236:237] op_sel_hi:[1,0]
	v_pk_mul_f32 v[2:3], v[2:3], v[236:237] op_sel_hi:[1,0]
	v_pk_mul_f32 v[0:1], v[0:1], v[128:129]
	v_pk_mul_f32 v[2:3], v[2:3], v[130:131]
	v_pk_fma_f32 v[0:1], v[0:1], v[160:161], v[192:193]
	v_pk_fma_f32 v[2:3], v[2:3], v[162:163], v[194:195]
	v_cvt_pk_bf16_f32 v0, v0, v1
	v_cvt_pk_bf16_f32 v1, v2, v3
	global_store_dwordx2 v234, v[0:1], s[22:23] offset:0
	v_pk_mul_f32 v[4:5], v[4:5], v[236:237] op_sel_hi:[1,0]
	v_pk_mul_f32 v[6:7], v[6:7], v[236:237] op_sel_hi:[1,0]
	v_pk_mul_f32 v[4:5], v[4:5], v[132:133]
	v_pk_mul_f32 v[6:7], v[6:7], v[134:135]
	v_pk_fma_f32 v[4:5], v[4:5], v[164:165], v[196:197]
	v_pk_fma_f32 v[6:7], v[6:7], v[166:167], v[198:199]
	v_cvt_pk_bf16_f32 v4, v4, v5
	v_cvt_pk_bf16_f32 v5, v6, v7
	global_store_dwordx2 v234, v[4:5], s[22:23] offset:512
	v_pk_mul_f32 v[8:9], v[8:9], v[236:237] op_sel_hi:[1,0]
	v_pk_mul_f32 v[10:11], v[10:11], v[236:237] op_sel_hi:[1,0]
	v_pk_mul_f32 v[8:9], v[8:9], v[136:137]
	v_pk_mul_f32 v[10:11], v[10:11], v[138:139]
	v_pk_fma_f32 v[8:9], v[8:9], v[168:169], v[200:201]
	v_pk_fma_f32 v[10:11], v[10:11], v[170:171], v[202:203]
	v_cvt_pk_bf16_f32 v8, v8, v9
	v_cvt_pk_bf16_f32 v9, v10, v11
	global_store_dwordx2 v234, v[8:9], s[22:23] offset:1024
	v_pk_mul_f32 v[12:13], v[12:13], v[236:237] op_sel_hi:[1,0]
	v_pk_mul_f32 v[14:15], v[14:15], v[236:237] op_sel_hi:[1,0]
	v_pk_mul_f32 v[12:13], v[12:13], v[140:141]
	v_pk_mul_f32 v[14:15], v[14:15], v[142:143]
	v_pk_fma_f32 v[12:13], v[12:13], v[172:173], v[204:205]
	v_pk_fma_f32 v[14:15], v[14:15], v[174:175], v[206:207]
	v_cvt_pk_bf16_f32 v12, v12, v13
	v_cvt_pk_bf16_f32 v13, v14, v15
	global_store_dwordx2 v234, v[12:13], s[22:23] offset:1536
	v_pk_mul_f32 v[16:17], v[16:17], v[236:237] op_sel_hi:[1,0]
	v_pk_mul_f32 v[18:19], v[18:19], v[236:237] op_sel_hi:[1,0]
	v_pk_mul_f32 v[16:17], v[16:17], v[144:145]
	v_pk_mul_f32 v[18:19], v[18:19], v[146:147]
	v_pk_fma_f32 v[16:17], v[16:17], v[176:177], v[208:209]
	v_pk_fma_f32 v[18:19], v[18:19], v[178:179], v[210:211]
	v_cvt_pk_bf16_f32 v16, v16, v17
	v_cvt_pk_bf16_f32 v17, v18, v19
	global_store_dwordx2 v234, v[16:17], s[22:23] offset:2048
	v_pk_mul_f32 v[20:21], v[20:21], v[236:237] op_sel_hi:[1,0]
	v_pk_mul_f32 v[22:23], v[22:23], v[236:237] op_sel_hi:[1,0]
	v_pk_mul_f32 v[20:21], v[20:21], v[148:149]
	v_pk_mul_f32 v[22:23], v[22:23], v[150:151]
	v_pk_fma_f32 v[20:21], v[20:21], v[180:181], v[212:213]
	v_pk_fma_f32 v[22:23], v[22:23], v[182:183], v[214:215]
	v_cvt_pk_bf16_f32 v20, v20, v21
	v_cvt_pk_bf16_f32 v21, v22, v23
	global_store_dwordx2 v234, v[20:21], s[22:23] offset:2560
	v_pk_mul_f32 v[24:25], v[24:25], v[236:237] op_sel_hi:[1,0]
	v_pk_mul_f32 v[26:27], v[26:27], v[236:237] op_sel_hi:[1,0]
	v_pk_mul_f32 v[24:25], v[24:25], v[152:153]
	v_pk_mul_f32 v[26:27], v[26:27], v[154:155]
	v_pk_fma_f32 v[24:25], v[24:25], v[184:185], v[216:217]
	v_pk_fma_f32 v[26:27], v[26:27], v[186:187], v[218:219]
	v_cvt_pk_bf16_f32 v24, v24, v25
	v_cvt_pk_bf16_f32 v25, v26, v27
	global_store_dwordx2 v234, v[24:25], s[22:23] offset:3072
	v_pk_mul_f32 v[28:29], v[28:29], v[236:237] op_sel_hi:[1,0]
	v_pk_mul_f32 v[30:31], v[30:31], v[236:237] op_sel_hi:[1,0]
	v_pk_mul_f32 v[28:29], v[28:29], v[156:157]
	v_pk_mul_f32 v[30:31], v[30:31], v[158:159]
	v_pk_fma_f32 v[28:29], v[28:29], v[188:189], v[220:221]
	v_pk_fma_f32 v[30:31], v[30:31], v[190:191], v[222:223]
	v_cvt_pk_bf16_f32 v28, v28, v29
	v_cvt_pk_bf16_f32 v29, v30, v31
	global_store_dwordx2 v234, v[28:29], s[22:23] offset:3584
	s_add_i32 s28, s8, 0x1800
	s_lshl_b32 s28, s28, 13
	s_add_u32 s20, s56, s28
	s_addc_u32 s21, s57, 0
	global_load_dwordx4 v[0:3], v232, s[20:21] offset:0 nt
	global_load_dwordx4 v[4:7], v232, s[20:21] offset:1024 nt
	global_load_dwordx4 v[8:11], v232, s[20:21] offset:2048 nt
	global_load_dwordx4 v[12:15], v232, s[20:21] offset:3072 nt
	global_load_dwordx4 v[16:19], v233, s[20:21] offset:0 nt
	global_load_dwordx4 v[20:23], v233, s[20:21] offset:1024 nt
	global_load_dwordx4 v[24:27], v233, s[20:21] offset:2048 nt
	global_load_dwordx4 v[28:31], v233, s[20:21] offset:3072 nt
	s_waitcnt vmcnt(24)
	v_pk_mul_f32 v[236:237], v[32:33], v[32:33]
	v_pk_fma_f32 v[236:237], v[34:35], v[34:35], v[236:237]
	v_pk_fma_f32 v[236:237], v[36:37], v[36:37], v[236:237]
	v_pk_fma_f32 v[236:237], v[38:39], v[38:39], v[236:237]
	v_pk_fma_f32 v[236:237], v[40:41], v[40:41], v[236:237]
	v_pk_fma_f32 v[236:237], v[42:43], v[42:43], v[236:237]
	v_pk_fma_f32 v[236:237], v[44:45], v[44:45], v[236:237]
	v_pk_fma_f32 v[236:237], v[46:47], v[46:47], v[236:237]
	v_pk_fma_f32 v[236:237], v[48:49], v[48:49], v[236:237]
	v_pk_fma_f32 v[236:237], v[50:51], v[50:51], v[236:237]
	v_pk_fma_f32 v[236:237], v[52:53], v[52:53], v[236:237]
	v_pk_fma_f32 v[236:237], v[54:55], v[54:55], v[236:237]
	v_pk_fma_f32 v[236:237], v[56:57], v[56:57], v[236:237]
	v_pk_fma_f32 v[236:237], v[58:59], v[58:59], v[236:237]
	v_pk_fma_f32 v[236:237], v[60:61], v[60:61], v[236:237]
	v_pk_fma_f32 v[236:237], v[62:63], v[62:63], v[236:237]
	v_add_f32_e32 v236, v236, v237
	ds_bpermute_b32 v237, v224, v236
	s_waitcnt lgkmcnt(0)
	v_add_f32_e32 v236, v236, v237
	ds_bpermute_b32 v237, v225, v236
	s_waitcnt lgkmcnt(0)
	v_add_f32_e32 v236, v236, v237
	ds_bpermute_b32 v237, v226, v236
	s_waitcnt lgkmcnt(0)
	v_add_f32_e32 v236, v236, v237
	ds_bpermute_b32 v237, v227, v236
	s_waitcnt lgkmcnt(0)
	v_add_f32_e32 v236, v236, v237
	ds_bpermute_b32 v237, v228, v236
	s_waitcnt lgkmcnt(0)
	v_add_f32_e32 v236, v236, v237
	ds_bpermute_b32 v237, v229, v236
	s_waitcnt lgkmcnt(0)
	v_add_f32_e32 v236, v236, v237
	v_fmamk_f32 v236, v236, 0x3a000000, v235
	v_rsq_f32_e32 v236, v236
	s_add_i32 s28, s8, 0x800
	s_lshl_b32 s28, s28, 12
	s_add_u32 s22, s76, s28
	s_addc_u32 s23, s77, 0
	s_add_u32 s22, s22, 0x7600000
	s_addc_u32 s23, s23, 0
	v_pk_mul_f32 v[32:33], v[32:33], v[236:237] op_sel_hi:[1,0]
	v_pk_mul_f32 v[34:35], v[34:35], v[236:237] op_sel_hi:[1,0]
	v_pk_mul_f32 v[32:33], v[32:33], v[128:129]
	v_pk_mul_f32 v[34:35], v[34:35], v[130:131]
	v_pk_fma_f32 v[32:33], v[32:33], v[160:161], v[192:193]
	v_pk_fma_f32 v[34:35], v[34:35], v[162:163], v[194:195]
	v_cvt_pk_bf16_f32 v32, v32, v33
	v_cvt_pk_bf16_f32 v33, v34, v35
	global_store_dwordx2 v234, v[32:33], s[22:23] offset:0
	v_pk_mul_f32 v[36:37], v[36:37], v[236:237] op_sel_hi:[1,0]
	v_pk_mul_f32 v[38:39], v[38:39], v[236:237] op_sel_hi:[1,0]
	v_pk_mul_f32 v[36:37], v[36:37], v[132:133]
	v_pk_mul_f32 v[38:39], v[38:39], v[134:135]
	v_pk_fma_f32 v[36:37], v[36:37], v[164:165], v[196:197]
	v_pk_fma_f32 v[38:39], v[38:39], v[166:167], v[198:199]
	v_cvt_pk_bf16_f32 v36, v36, v37
	v_cvt_pk_bf16_f32 v37, v38, v39
	global_store_dwordx2 v234, v[36:37], s[22:23] offset:512
	v_pk_mul_f32 v[40:41], v[40:41], v[236:237] op_sel_hi:[1,0]
	v_pk_mul_f32 v[42:43], v[42:43], v[236:237] op_sel_hi:[1,0]
	v_pk_mul_f32 v[40:41], v[40:41], v[136:137]
	v_pk_mul_f32 v[42:43], v[42:43], v[138:139]
	v_pk_fma_f32 v[40:41], v[40:41], v[168:169], v[200:201]
	v_pk_fma_f32 v[42:43], v[42:43], v[170:171], v[202:203]
	v_cvt_pk_bf16_f32 v40, v40, v41
	v_cvt_pk_bf16_f32 v41, v42, v43
	global_store_dwordx2 v234, v[40:41], s[22:23] offset:1024
	v_pk_mul_f32 v[44:45], v[44:45], v[236:237] op_sel_hi:[1,0]
	v_pk_mul_f32 v[46:47], v[46:47], v[236:237] op_sel_hi:[1,0]
	v_pk_mul_f32 v[44:45], v[44:45], v[140:141]
	v_pk_mul_f32 v[46:47], v[46:47], v[142:143]
	v_pk_fma_f32 v[44:45], v[44:45], v[172:173], v[204:205]
	v_pk_fma_f32 v[46:47], v[46:47], v[174:175], v[206:207]
	v_cvt_pk_bf16_f32 v44, v44, v45
	v_cvt_pk_bf16_f32 v45, v46, v47
	global_store_dwordx2 v234, v[44:45], s[22:23] offset:1536
	v_pk_mul_f32 v[48:49], v[48:49], v[236:237] op_sel_hi:[1,0]
	v_pk_mul_f32 v[50:51], v[50:51], v[236:237] op_sel_hi:[1,0]
	v_pk_mul_f32 v[48:49], v[48:49], v[144:145]
	v_pk_mul_f32 v[50:51], v[50:51], v[146:147]
	v_pk_fma_f32 v[48:49], v[48:49], v[176:177], v[208:209]
	v_pk_fma_f32 v[50:51], v[50:51], v[178:179], v[210:211]
	v_cvt_pk_bf16_f32 v48, v48, v49
	v_cvt_pk_bf16_f32 v49, v50, v51
	global_store_dwordx2 v234, v[48:49], s[22:23] offset:2048
	v_pk_mul_f32 v[52:53], v[52:53], v[236:237] op_sel_hi:[1,0]
	v_pk_mul_f32 v[54:55], v[54:55], v[236:237] op_sel_hi:[1,0]
	v_pk_mul_f32 v[52:53], v[52:53], v[148:149]
	v_pk_mul_f32 v[54:55], v[54:55], v[150:151]
	v_pk_fma_f32 v[52:53], v[52:53], v[180:181], v[212:213]
	v_pk_fma_f32 v[54:55], v[54:55], v[182:183], v[214:215]
	v_cvt_pk_bf16_f32 v52, v52, v53
	v_cvt_pk_bf16_f32 v53, v54, v55
	global_store_dwordx2 v234, v[52:53], s[22:23] offset:2560
	v_pk_mul_f32 v[56:57], v[56:57], v[236:237] op_sel_hi:[1,0]
	v_pk_mul_f32 v[58:59], v[58:59], v[236:237] op_sel_hi:[1,0]
	v_pk_mul_f32 v[56:57], v[56:57], v[152:153]
	v_pk_mul_f32 v[58:59], v[58:59], v[154:155]
	v_pk_fma_f32 v[56:57], v[56:57], v[184:185], v[216:217]
	v_pk_fma_f32 v[58:59], v[58:59], v[186:187], v[218:219]
	v_cvt_pk_bf16_f32 v56, v56, v57
	v_cvt_pk_bf16_f32 v57, v58, v59
	global_store_dwordx2 v234, v[56:57], s[22:23] offset:3072
	v_pk_mul_f32 v[60:61], v[60:61], v[236:237] op_sel_hi:[1,0]
	v_pk_mul_f32 v[62:63], v[62:63], v[236:237] op_sel_hi:[1,0]
	v_pk_mul_f32 v[60:61], v[60:61], v[156:157]
	v_pk_mul_f32 v[62:63], v[62:63], v[158:159]
	v_pk_fma_f32 v[60:61], v[60:61], v[188:189], v[220:221]
	v_pk_fma_f32 v[62:63], v[62:63], v[190:191], v[222:223]
	v_cvt_pk_bf16_f32 v60, v60, v61
	v_cvt_pk_bf16_f32 v61, v62, v63
	global_store_dwordx2 v234, v[60:61], s[22:23] offset:3584
	s_lshl_b32 s28, s8, 13
	s_add_u32 s20, s58, s28
	s_addc_u32 s21, s59, 0
	global_load_dwordx4 v[32:35], v232, s[20:21] offset:0 nt
	global_load_dwordx4 v[36:39], v232, s[20:21] offset:1024 nt
	global_load_dwordx4 v[40:43], v232, s[20:21] offset:2048 nt
	global_load_dwordx4 v[44:47], v232, s[20:21] offset:3072 nt
	global_load_dwordx4 v[48:51], v233, s[20:21] offset:0 nt
	global_load_dwordx4 v[52:55], v233, s[20:21] offset:1024 nt
	global_load_dwordx4 v[56:59], v233, s[20:21] offset:2048 nt
	global_load_dwordx4 v[60:63], v233, s[20:21] offset:3072 nt
	s_waitcnt vmcnt(32)
	v_pk_mul_f32 v[236:237], v[64:65], v[64:65]
	v_pk_fma_f32 v[236:237], v[66:67], v[66:67], v[236:237]
	v_pk_fma_f32 v[236:237], v[68:69], v[68:69], v[236:237]
	v_pk_fma_f32 v[236:237], v[70:71], v[70:71], v[236:237]
	v_pk_fma_f32 v[236:237], v[72:73], v[72:73], v[236:237]
	v_pk_fma_f32 v[236:237], v[74:75], v[74:75], v[236:237]
	v_pk_fma_f32 v[236:237], v[76:77], v[76:77], v[236:237]
	v_pk_fma_f32 v[236:237], v[78:79], v[78:79], v[236:237]
	v_pk_fma_f32 v[236:237], v[80:81], v[80:81], v[236:237]
	v_pk_fma_f32 v[236:237], v[82:83], v[82:83], v[236:237]
	v_pk_fma_f32 v[236:237], v[84:85], v[84:85], v[236:237]
	v_pk_fma_f32 v[236:237], v[86:87], v[86:87], v[236:237]
	v_pk_fma_f32 v[236:237], v[88:89], v[88:89], v[236:237]
	v_pk_fma_f32 v[236:237], v[90:91], v[90:91], v[236:237]
	v_pk_fma_f32 v[236:237], v[92:93], v[92:93], v[236:237]
	v_pk_fma_f32 v[236:237], v[94:95], v[94:95], v[236:237]
	v_add_f32_e32 v236, v236, v237
	ds_bpermute_b32 v237, v224, v236
	s_waitcnt lgkmcnt(0)
	v_add_f32_e32 v236, v236, v237
	ds_bpermute_b32 v237, v225, v236
	s_waitcnt lgkmcnt(0)
	v_add_f32_e32 v236, v236, v237
	ds_bpermute_b32 v237, v226, v236
	s_waitcnt lgkmcnt(0)
	v_add_f32_e32 v236, v236, v237
	ds_bpermute_b32 v237, v227, v236
	s_waitcnt lgkmcnt(0)
	v_add_f32_e32 v236, v236, v237
	ds_bpermute_b32 v237, v228, v236
	s_waitcnt lgkmcnt(0)
	v_add_f32_e32 v236, v236, v237
	ds_bpermute_b32 v237, v229, v236
	s_waitcnt lgkmcnt(0)
	v_add_f32_e32 v236, v236, v237
	v_fmamk_f32 v236, v236, 0x3a000000, v235
	v_rsq_f32_e32 v236, v236
	s_add_i32 s28, s8, 0x1000
	s_lshl_b32 s28, s28, 12
	s_add_u32 s22, s76, s28
	s_addc_u32 s23, s77, 0
	s_add_u32 s22, s22, 0x7600000
	s_addc_u32 s23, s23, 0
	v_pk_mul_f32 v[64:65], v[64:65], v[236:237] op_sel_hi:[1,0]
	v_pk_mul_f32 v[66:67], v[66:67], v[236:237] op_sel_hi:[1,0]
	v_pk_mul_f32 v[64:65], v[64:65], v[128:129]
	v_pk_mul_f32 v[66:67], v[66:67], v[130:131]
	v_pk_fma_f32 v[64:65], v[64:65], v[160:161], v[192:193]
	v_pk_fma_f32 v[66:67], v[66:67], v[162:163], v[194:195]
	v_cvt_pk_bf16_f32 v64, v64, v65
	v_cvt_pk_bf16_f32 v65, v66, v67
	global_store_dwordx2 v234, v[64:65], s[22:23] offset:0
	v_pk_mul_f32 v[68:69], v[68:69], v[236:237] op_sel_hi:[1,0]
	v_pk_mul_f32 v[70:71], v[70:71], v[236:237] op_sel_hi:[1,0]
	v_pk_mul_f32 v[68:69], v[68:69], v[132:133]
	v_pk_mul_f32 v[70:71], v[70:71], v[134:135]
	v_pk_fma_f32 v[68:69], v[68:69], v[164:165], v[196:197]
	v_pk_fma_f32 v[70:71], v[70:71], v[166:167], v[198:199]
	v_cvt_pk_bf16_f32 v68, v68, v69
	v_cvt_pk_bf16_f32 v69, v70, v71
	global_store_dwordx2 v234, v[68:69], s[22:23] offset:512
	v_pk_mul_f32 v[72:73], v[72:73], v[236:237] op_sel_hi:[1,0]
	v_pk_mul_f32 v[74:75], v[74:75], v[236:237] op_sel_hi:[1,0]
	v_pk_mul_f32 v[72:73], v[72:73], v[136:137]
	v_pk_mul_f32 v[74:75], v[74:75], v[138:139]
	v_pk_fma_f32 v[72:73], v[72:73], v[168:169], v[200:201]
	v_pk_fma_f32 v[74:75], v[74:75], v[170:171], v[202:203]
	v_cvt_pk_bf16_f32 v72, v72, v73
	v_cvt_pk_bf16_f32 v73, v74, v75
	global_store_dwordx2 v234, v[72:73], s[22:23] offset:1024
	v_pk_mul_f32 v[76:77], v[76:77], v[236:237] op_sel_hi:[1,0]
	v_pk_mul_f32 v[78:79], v[78:79], v[236:237] op_sel_hi:[1,0]
	v_pk_mul_f32 v[76:77], v[76:77], v[140:141]
	v_pk_mul_f32 v[78:79], v[78:79], v[142:143]
	v_pk_fma_f32 v[76:77], v[76:77], v[172:173], v[204:205]
	v_pk_fma_f32 v[78:79], v[78:79], v[174:175], v[206:207]
	v_cvt_pk_bf16_f32 v76, v76, v77
	v_cvt_pk_bf16_f32 v77, v78, v79
	global_store_dwordx2 v234, v[76:77], s[22:23] offset:1536
	v_pk_mul_f32 v[80:81], v[80:81], v[236:237] op_sel_hi:[1,0]
	v_pk_mul_f32 v[82:83], v[82:83], v[236:237] op_sel_hi:[1,0]
	v_pk_mul_f32 v[80:81], v[80:81], v[144:145]
	v_pk_mul_f32 v[82:83], v[82:83], v[146:147]
	v_pk_fma_f32 v[80:81], v[80:81], v[176:177], v[208:209]
	v_pk_fma_f32 v[82:83], v[82:83], v[178:179], v[210:211]
	v_cvt_pk_bf16_f32 v80, v80, v81
	v_cvt_pk_bf16_f32 v81, v82, v83
	global_store_dwordx2 v234, v[80:81], s[22:23] offset:2048
	v_pk_mul_f32 v[84:85], v[84:85], v[236:237] op_sel_hi:[1,0]
	v_pk_mul_f32 v[86:87], v[86:87], v[236:237] op_sel_hi:[1,0]
	v_pk_mul_f32 v[84:85], v[84:85], v[148:149]
	v_pk_mul_f32 v[86:87], v[86:87], v[150:151]
	v_pk_fma_f32 v[84:85], v[84:85], v[180:181], v[212:213]
	v_pk_fma_f32 v[86:87], v[86:87], v[182:183], v[214:215]
	v_cvt_pk_bf16_f32 v84, v84, v85
	v_cvt_pk_bf16_f32 v85, v86, v87
	global_store_dwordx2 v234, v[84:85], s[22:23] offset:2560
	v_pk_mul_f32 v[88:89], v[88:89], v[236:237] op_sel_hi:[1,0]
	v_pk_mul_f32 v[90:91], v[90:91], v[236:237] op_sel_hi:[1,0]
	v_pk_mul_f32 v[88:89], v[88:89], v[152:153]
	v_pk_mul_f32 v[90:91], v[90:91], v[154:155]
	v_pk_fma_f32 v[88:89], v[88:89], v[184:185], v[216:217]
	v_pk_fma_f32 v[90:91], v[90:91], v[186:187], v[218:219]
	v_cvt_pk_bf16_f32 v88, v88, v89
	v_cvt_pk_bf16_f32 v89, v90, v91
	global_store_dwordx2 v234, v[88:89], s[22:23] offset:3072
	v_pk_mul_f32 v[92:93], v[92:93], v[236:237] op_sel_hi:[1,0]
	v_pk_mul_f32 v[94:95], v[94:95], v[236:237] op_sel_hi:[1,0]
	v_pk_mul_f32 v[92:93], v[92:93], v[156:157]
	v_pk_mul_f32 v[94:95], v[94:95], v[158:159]
	v_pk_fma_f32 v[92:93], v[92:93], v[188:189], v[220:221]
	v_pk_fma_f32 v[94:95], v[94:95], v[190:191], v[222:223]
	v_cvt_pk_bf16_f32 v92, v92, v93
	v_cvt_pk_bf16_f32 v93, v94, v95
	global_store_dwordx2 v234, v[92:93], s[22:23] offset:3584
	s_lshr_b32 s28, s8, 10
	s_add_i32 s28, s28, 1
	s_mul_i32 s28, s28, 0xc000
	s_add_u32 s26, s76, s28
	s_addc_u32 s27, s77, 0
	s_add_u32 s24, s26, 0x2000
	s_addc_u32 s25, s27, 0
	global_load_dwordx4 v[96:99], v232, s[24:25] offset:0
	global_load_dwordx4 v[100:103], v232, s[24:25] offset:1024
	global_load_dwordx4 v[104:107], v232, s[24:25] offset:2048
	global_load_dwordx4 v[108:111], v232, s[24:25] offset:3072
	global_load_dwordx4 v[112:115], v233, s[24:25] offset:0
	global_load_dwordx4 v[116:119], v233, s[24:25] offset:1024
	global_load_dwordx4 v[120:123], v233, s[24:25] offset:2048
	global_load_dwordx4 v[124:127], v233, s[24:25] offset:3072
	global_load_dwordx4 v[64:67], v232, s[26:27] offset:0
	global_load_dwordx4 v[68:71], v232, s[26:27] offset:1024
	global_load_dwordx4 v[72:75], v232, s[26:27] offset:2048
	global_load_dwordx4 v[76:79], v232, s[26:27] offset:3072
	global_load_dwordx4 v[80:83], v233, s[26:27] offset:0
	global_load_dwordx4 v[84:87], v233, s[26:27] offset:1024
	global_load_dwordx4 v[88:91], v233, s[26:27] offset:2048
	global_load_dwordx4 v[92:95], v233, s[26:27] offset:3072
	s_waitcnt vmcnt(40)
	v_pk_mul_f32 v[236:237], v[0:1], v[0:1]
	v_pk_fma_f32 v[236:237], v[2:3], v[2:3], v[236:237]
	v_pk_fma_f32 v[236:237], v[4:5], v[4:5], v[236:237]
	v_pk_fma_f32 v[236:237], v[6:7], v[6:7], v[236:237]
	v_pk_fma_f32 v[236:237], v[8:9], v[8:9], v[236:237]
	v_pk_fma_f32 v[236:237], v[10:11], v[10:11], v[236:237]
	v_pk_fma_f32 v[236:237], v[12:13], v[12:13], v[236:237]
	v_pk_fma_f32 v[236:237], v[14:15], v[14:15], v[236:237]
	v_pk_fma_f32 v[236:237], v[16:17], v[16:17], v[236:237]
	v_pk_fma_f32 v[236:237], v[18:19], v[18:19], v[236:237]
	v_pk_fma_f32 v[236:237], v[20:21], v[20:21], v[236:237]
	v_pk_fma_f32 v[236:237], v[22:23], v[22:23], v[236:237]
	v_pk_fma_f32 v[236:237], v[24:25], v[24:25], v[236:237]
	v_pk_fma_f32 v[236:237], v[26:27], v[26:27], v[236:237]
	v_pk_fma_f32 v[236:237], v[28:29], v[28:29], v[236:237]
	v_pk_fma_f32 v[236:237], v[30:31], v[30:31], v[236:237]
	v_add_f32_e32 v236, v236, v237
	ds_bpermute_b32 v237, v224, v236
	s_waitcnt lgkmcnt(0)
	v_add_f32_e32 v236, v236, v237
	ds_bpermute_b32 v237, v225, v236
	s_waitcnt lgkmcnt(0)
	v_add_f32_e32 v236, v236, v237
	ds_bpermute_b32 v237, v226, v236
	s_waitcnt lgkmcnt(0)
	v_add_f32_e32 v236, v236, v237
	ds_bpermute_b32 v237, v227, v236
	s_waitcnt lgkmcnt(0)
	v_add_f32_e32 v236, v236, v237
	ds_bpermute_b32 v237, v228, v236
	s_waitcnt lgkmcnt(0)
	v_add_f32_e32 v236, v236, v237
	ds_bpermute_b32 v237, v229, v236
	s_waitcnt lgkmcnt(0)
	v_add_f32_e32 v236, v236, v237
	v_fmamk_f32 v236, v236, 0x3a000000, v235
	v_rsq_f32_e32 v236, v236
	s_add_i32 s28, s8, 0x1800
	s_lshl_b32 s28, s28, 12
	s_add_u32 s22, s76, s28
	s_addc_u32 s23, s77, 0
	s_add_u32 s22, s22, 0x7600000
	s_addc_u32 s23, s23, 0
	v_pk_mul_f32 v[0:1], v[0:1], v[236:237] op_sel_hi:[1,0]
	v_pk_mul_f32 v[2:3], v[2:3], v[236:237] op_sel_hi:[1,0]
	v_pk_mul_f32 v[0:1], v[0:1], v[128:129]
	v_pk_mul_f32 v[2:3], v[2:3], v[130:131]
	v_pk_fma_f32 v[0:1], v[0:1], v[160:161], v[192:193]
	v_pk_fma_f32 v[2:3], v[2:3], v[162:163], v[194:195]
	v_cvt_pk_bf16_f32 v0, v0, v1
	v_cvt_pk_bf16_f32 v1, v2, v3
	global_store_dwordx2 v234, v[0:1], s[22:23] offset:0
	v_pk_mul_f32 v[4:5], v[4:5], v[236:237] op_sel_hi:[1,0]
	v_pk_mul_f32 v[6:7], v[6:7], v[236:237] op_sel_hi:[1,0]
	v_pk_mul_f32 v[4:5], v[4:5], v[132:133]
	v_pk_mul_f32 v[6:7], v[6:7], v[134:135]
	v_pk_fma_f32 v[4:5], v[4:5], v[164:165], v[196:197]
	v_pk_fma_f32 v[6:7], v[6:7], v[166:167], v[198:199]
	v_cvt_pk_bf16_f32 v4, v4, v5
	v_cvt_pk_bf16_f32 v5, v6, v7
	global_store_dwordx2 v234, v[4:5], s[22:23] offset:512
	v_pk_mul_f32 v[8:9], v[8:9], v[236:237] op_sel_hi:[1,0]
	v_pk_mul_f32 v[10:11], v[10:11], v[236:237] op_sel_hi:[1,0]
	v_pk_mul_f32 v[8:9], v[8:9], v[136:137]
	v_pk_mul_f32 v[10:11], v[10:11], v[138:139]
	v_pk_fma_f32 v[8:9], v[8:9], v[168:169], v[200:201]
	v_pk_fma_f32 v[10:11], v[10:11], v[170:171], v[202:203]
	v_cvt_pk_bf16_f32 v8, v8, v9
	v_cvt_pk_bf16_f32 v9, v10, v11
	global_store_dwordx2 v234, v[8:9], s[22:23] offset:1024
	v_pk_mul_f32 v[12:13], v[12:13], v[236:237] op_sel_hi:[1,0]
	v_pk_mul_f32 v[14:15], v[14:15], v[236:237] op_sel_hi:[1,0]
	v_pk_mul_f32 v[12:13], v[12:13], v[140:141]
	v_pk_mul_f32 v[14:15], v[14:15], v[142:143]
	v_pk_fma_f32 v[12:13], v[12:13], v[172:173], v[204:205]
	v_pk_fma_f32 v[14:15], v[14:15], v[174:175], v[206:207]
	v_cvt_pk_bf16_f32 v12, v12, v13
	v_cvt_pk_bf16_f32 v13, v14, v15
	global_store_dwordx2 v234, v[12:13], s[22:23] offset:1536
	v_pk_mul_f32 v[16:17], v[16:17], v[236:237] op_sel_hi:[1,0]
	v_pk_mul_f32 v[18:19], v[18:19], v[236:237] op_sel_hi:[1,0]
	v_pk_mul_f32 v[16:17], v[16:17], v[144:145]
	v_pk_mul_f32 v[18:19], v[18:19], v[146:147]
	v_pk_fma_f32 v[16:17], v[16:17], v[176:177], v[208:209]
	v_pk_fma_f32 v[18:19], v[18:19], v[178:179], v[210:211]
	v_cvt_pk_bf16_f32 v16, v16, v17
	v_cvt_pk_bf16_f32 v17, v18, v19
	global_store_dwordx2 v234, v[16:17], s[22:23] offset:2048
	v_pk_mul_f32 v[20:21], v[20:21], v[236:237] op_sel_hi:[1,0]
	v_pk_mul_f32 v[22:23], v[22:23], v[236:237] op_sel_hi:[1,0]
	v_pk_mul_f32 v[20:21], v[20:21], v[148:149]
	v_pk_mul_f32 v[22:23], v[22:23], v[150:151]
	v_pk_fma_f32 v[20:21], v[20:21], v[180:181], v[212:213]
	v_pk_fma_f32 v[22:23], v[22:23], v[182:183], v[214:215]
	v_cvt_pk_bf16_f32 v20, v20, v21
	v_cvt_pk_bf16_f32 v21, v22, v23
	global_store_dwordx2 v234, v[20:21], s[22:23] offset:2560
	v_pk_mul_f32 v[24:25], v[24:25], v[236:237] op_sel_hi:[1,0]
	v_pk_mul_f32 v[26:27], v[26:27], v[236:237] op_sel_hi:[1,0]
	v_pk_mul_f32 v[24:25], v[24:25], v[152:153]
	v_pk_mul_f32 v[26:27], v[26:27], v[154:155]
	v_pk_fma_f32 v[24:25], v[24:25], v[184:185], v[216:217]
	v_pk_fma_f32 v[26:27], v[26:27], v[186:187], v[218:219]
	v_cvt_pk_bf16_f32 v24, v24, v25
	v_cvt_pk_bf16_f32 v25, v26, v27
	global_store_dwordx2 v234, v[24:25], s[22:23] offset:3072
	v_pk_mul_f32 v[28:29], v[28:29], v[236:237] op_sel_hi:[1,0]
	v_pk_mul_f32 v[30:31], v[30:31], v[236:237] op_sel_hi:[1,0]
	v_pk_mul_f32 v[28:29], v[28:29], v[156:157]
	v_pk_mul_f32 v[30:31], v[30:31], v[158:159]
	v_pk_fma_f32 v[28:29], v[28:29], v[188:189], v[220:221]
	v_pk_fma_f32 v[30:31], v[30:31], v[190:191], v[222:223]
	v_cvt_pk_bf16_f32 v28, v28, v29
	v_cvt_pk_bf16_f32 v29, v30, v31
	global_store_dwordx2 v234, v[28:29], s[22:23] offset:3584
	s_waitcnt vmcnt(8)
	v_pk_add_f32 v[96:97], v[96:97], 1.0 op_sel_hi:[1,0]
	v_pk_add_f32 v[98:99], v[98:99], 1.0 op_sel_hi:[1,0]
	v_pk_add_f32 v[100:101], v[100:101], 1.0 op_sel_hi:[1,0]
	v_pk_add_f32 v[102:103], v[102:103], 1.0 op_sel_hi:[1,0]
	v_pk_add_f32 v[104:105], v[104:105], 1.0 op_sel_hi:[1,0]
	v_pk_add_f32 v[106:107], v[106:107], 1.0 op_sel_hi:[1,0]
	v_pk_add_f32 v[108:109], v[108:109], 1.0 op_sel_hi:[1,0]
	v_pk_add_f32 v[110:111], v[110:111], 1.0 op_sel_hi:[1,0]
	v_pk_add_f32 v[112:113], v[112:113], 1.0 op_sel_hi:[1,0]
	v_pk_add_f32 v[114:115], v[114:115], 1.0 op_sel_hi:[1,0]
	v_pk_add_f32 v[116:117], v[116:117], 1.0 op_sel_hi:[1,0]
	v_pk_add_f32 v[118:119], v[118:119], 1.0 op_sel_hi:[1,0]
	v_pk_add_f32 v[120:121], v[120:121], 1.0 op_sel_hi:[1,0]
	v_pk_add_f32 v[122:123], v[122:123], 1.0 op_sel_hi:[1,0]
	v_pk_add_f32 v[124:125], v[124:125], 1.0 op_sel_hi:[1,0]
	v_pk_add_f32 v[126:127], v[126:127], 1.0 op_sel_hi:[1,0]
	v_pk_mul_f32 v[236:237], v[32:33], v[32:33]
	v_pk_fma_f32 v[236:237], v[34:35], v[34:35], v[236:237]
	v_pk_fma_f32 v[236:237], v[36:37], v[36:37], v[236:237]
	v_pk_fma_f32 v[236:237], v[38:39], v[38:39], v[236:237]
	v_pk_fma_f32 v[236:237], v[40:41], v[40:41], v[236:237]
	v_pk_fma_f32 v[236:237], v[42:43], v[42:43], v[236:237]
	v_pk_fma_f32 v[236:237], v[44:45], v[44:45], v[236:237]
	v_pk_fma_f32 v[236:237], v[46:47], v[46:47], v[236:237]
	v_pk_fma_f32 v[236:237], v[48:49], v[48:49], v[236:237]
	v_pk_fma_f32 v[236:237], v[50:51], v[50:51], v[236:237]
	v_pk_fma_f32 v[236:237], v[52:53], v[52:53], v[236:237]
	v_pk_fma_f32 v[236:237], v[54:55], v[54:55], v[236:237]
	v_pk_fma_f32 v[236:237], v[56:57], v[56:57], v[236:237]
	v_pk_fma_f32 v[236:237], v[58:59], v[58:59], v[236:237]
	v_pk_fma_f32 v[236:237], v[60:61], v[60:61], v[236:237]
	v_pk_fma_f32 v[236:237], v[62:63], v[62:63], v[236:237]
	v_add_f32_e32 v236, v236, v237
	ds_bpermute_b32 v237, v224, v236
	s_waitcnt lgkmcnt(0)
	v_add_f32_e32 v236, v236, v237
	ds_bpermute_b32 v237, v225, v236
	s_waitcnt lgkmcnt(0)
	v_add_f32_e32 v236, v236, v237
	ds_bpermute_b32 v237, v226, v236
	s_waitcnt lgkmcnt(0)
	v_add_f32_e32 v236, v236, v237
	ds_bpermute_b32 v237, v227, v236
	s_waitcnt lgkmcnt(0)
	v_add_f32_e32 v236, v236, v237
	ds_bpermute_b32 v237, v228, v236
	s_waitcnt lgkmcnt(0)
	v_add_f32_e32 v236, v236, v237
	ds_bpermute_b32 v237, v229, v236
	s_waitcnt lgkmcnt(0)
	v_add_f32_e32 v236, v236, v237
	v_fmamk_f32 v236, v236, 0x3a000000, v235
	v_rsq_f32_e32 v236, v236
	s_add_i32 s28, s8, 0x2000
	s_lshl_b32 s28, s28, 12
	s_add_u32 s22, s76, s28
	s_addc_u32 s23, s77, 0
	s_add_u32 s22, s22, 0x7600000
	s_addc_u32 s23, s23, 0
	v_pk_mul_f32 v[32:33], v[32:33], v[236:237] op_sel_hi:[1,0]
	v_pk_mul_f32 v[34:35], v[34:35], v[236:237] op_sel_hi:[1,0]
	v_pk_mul_f32 v[32:33], v[32:33], v[128:129]
	v_pk_mul_f32 v[34:35], v[34:35], v[130:131]
	v_pk_fma_f32 v[32:33], v[32:33], v[96:97], v[64:65]
	v_pk_fma_f32 v[34:35], v[34:35], v[98:99], v[66:67]
	v_cvt_pk_bf16_f32 v32, v32, v33
	v_cvt_pk_bf16_f32 v33, v34, v35
	global_store_dwordx2 v234, v[32:33], s[22:23] offset:0
	v_pk_mul_f32 v[36:37], v[36:37], v[236:237] op_sel_hi:[1,0]
	v_pk_mul_f32 v[38:39], v[38:39], v[236:237] op_sel_hi:[1,0]
	v_pk_mul_f32 v[36:37], v[36:37], v[132:133]
	v_pk_mul_f32 v[38:39], v[38:39], v[134:135]
	v_pk_fma_f32 v[36:37], v[36:37], v[100:101], v[68:69]
	v_pk_fma_f32 v[38:39], v[38:39], v[102:103], v[70:71]
	v_cvt_pk_bf16_f32 v36, v36, v37
	v_cvt_pk_bf16_f32 v37, v38, v39
	global_store_dwordx2 v234, v[36:37], s[22:23] offset:512
	v_pk_mul_f32 v[40:41], v[40:41], v[236:237] op_sel_hi:[1,0]
	v_pk_mul_f32 v[42:43], v[42:43], v[236:237] op_sel_hi:[1,0]
	v_pk_mul_f32 v[40:41], v[40:41], v[136:137]
	v_pk_mul_f32 v[42:43], v[42:43], v[138:139]
	v_pk_fma_f32 v[40:41], v[40:41], v[104:105], v[72:73]
	v_pk_fma_f32 v[42:43], v[42:43], v[106:107], v[74:75]
	v_cvt_pk_bf16_f32 v40, v40, v41
	v_cvt_pk_bf16_f32 v41, v42, v43
	global_store_dwordx2 v234, v[40:41], s[22:23] offset:1024
	v_pk_mul_f32 v[44:45], v[44:45], v[236:237] op_sel_hi:[1,0]
	v_pk_mul_f32 v[46:47], v[46:47], v[236:237] op_sel_hi:[1,0]
	v_pk_mul_f32 v[44:45], v[44:45], v[140:141]
	v_pk_mul_f32 v[46:47], v[46:47], v[142:143]
	v_pk_fma_f32 v[44:45], v[44:45], v[108:109], v[76:77]
	v_pk_fma_f32 v[46:47], v[46:47], v[110:111], v[78:79]
	v_cvt_pk_bf16_f32 v44, v44, v45
	v_cvt_pk_bf16_f32 v45, v46, v47
	global_store_dwordx2 v234, v[44:45], s[22:23] offset:1536
	v_pk_mul_f32 v[48:49], v[48:49], v[236:237] op_sel_hi:[1,0]
	v_pk_mul_f32 v[50:51], v[50:51], v[236:237] op_sel_hi:[1,0]
	v_pk_mul_f32 v[48:49], v[48:49], v[144:145]
	v_pk_mul_f32 v[50:51], v[50:51], v[146:147]
	v_pk_fma_f32 v[48:49], v[48:49], v[112:113], v[80:81]
	v_pk_fma_f32 v[50:51], v[50:51], v[114:115], v[82:83]
	v_cvt_pk_bf16_f32 v48, v48, v49
	v_cvt_pk_bf16_f32 v49, v50, v51
	global_store_dwordx2 v234, v[48:49], s[22:23] offset:2048
	v_pk_mul_f32 v[52:53], v[52:53], v[236:237] op_sel_hi:[1,0]
	v_pk_mul_f32 v[54:55], v[54:55], v[236:237] op_sel_hi:[1,0]
	v_pk_mul_f32 v[52:53], v[52:53], v[148:149]
	v_pk_mul_f32 v[54:55], v[54:55], v[150:151]
	v_pk_fma_f32 v[52:53], v[52:53], v[116:117], v[84:85]
	v_pk_fma_f32 v[54:55], v[54:55], v[118:119], v[86:87]
	v_cvt_pk_bf16_f32 v52, v52, v53
	v_cvt_pk_bf16_f32 v53, v54, v55
	global_store_dwordx2 v234, v[52:53], s[22:23] offset:2560
	v_pk_mul_f32 v[56:57], v[56:57], v[236:237] op_sel_hi:[1,0]
	v_pk_mul_f32 v[58:59], v[58:59], v[236:237] op_sel_hi:[1,0]
	v_pk_mul_f32 v[56:57], v[56:57], v[152:153]
	v_pk_mul_f32 v[58:59], v[58:59], v[154:155]
	v_pk_fma_f32 v[56:57], v[56:57], v[120:121], v[88:89]
	v_pk_fma_f32 v[58:59], v[58:59], v[122:123], v[90:91]
	v_cvt_pk_bf16_f32 v56, v56, v57
	v_cvt_pk_bf16_f32 v57, v58, v59
	global_store_dwordx2 v234, v[56:57], s[22:23] offset:3072
	v_pk_mul_f32 v[60:61], v[60:61], v[236:237] op_sel_hi:[1,0]
	v_pk_mul_f32 v[62:63], v[62:63], v[236:237] op_sel_hi:[1,0]
	v_pk_mul_f32 v[60:61], v[60:61], v[156:157]
	v_pk_mul_f32 v[62:63], v[62:63], v[158:159]
	v_pk_fma_f32 v[60:61], v[60:61], v[124:125], v[92:93]
	v_pk_fma_f32 v[62:63], v[62:63], v[126:127], v[94:95]
	v_cvt_pk_bf16_f32 v60, v60, v61
	v_cvt_pk_bf16_f32 v61, v62, v63
	global_store_dwordx2 v234, v[60:61], s[22:23] offset:3584
	s_branch .LBB0_118
.Lp1_generic:
	v_readfirstlane_b32 s9, v243
	s_lshl_b32 s8, s96, 3
	s_lshr_b32 s9, s9, 6
	s_add_i32 s8, s9, s8
	s_cmpk_gt_i32 s8, 0x27ff
	s_cbranch_scc1 .LBB0_118
	v_mbcnt_lo_u32_b32 v1, -1, 0
	v_mbcnt_hi_u32_b32 v1, -1, v1
	v_and_b32_e32 v3, 64, v1
	v_add_u32_e32 v3, 64, v3
	v_xor_b32_e32 v5, 1, v1
	v_cmp_lt_i32_e32 vcc, v5, v3
	v_lshlrev_b32_e32 v0, 2, v243
	v_and_b32_e32 v0, 0xfc, v0
	v_cndmask_b32_e32 v5, v1, v5, vcc
	v_lshlrev_b32_e32 v76, 2, v5
	v_xor_b32_e32 v5, 2, v1
	v_cmp_lt_i32_e32 vcc, v5, v3
	v_mov_b32_e32 v61, 0
	v_lshlrev_b32_e32 v60, 2, v0
	v_cndmask_b32_e32 v5, v1, v5, vcc
	v_or_b32_e32 v8, 0x400, v0
	v_lshlrev_b32_e32 v77, 2, v5
	v_xor_b32_e32 v5, 4, v1
	v_lshl_add_u64 v[62:63], s[4:5], 0, v[60:61]
	v_lshlrev_b32_e32 v60, 2, v8
	v_or_b32_e32 v10, 0x500, v0
	v_cmp_lt_i32_e32 vcc, v5, v3
	v_lshl_add_u64 v[64:65], s[4:5], 0, v[60:61]
	v_lshlrev_b32_e32 v60, 2, v10
	v_or_b32_e32 v12, 0x600, v0
	v_cndmask_b32_e32 v5, v1, v5, vcc
	v_lshl_add_u64 v[66:67], s[4:5], 0, v[60:61]
	v_lshlrev_b32_e32 v60, 2, v12
	v_or_b32_e32 v14, 0x700, v0
	v_lshlrev_b32_e32 v78, 2, v5
	v_xor_b32_e32 v5, 8, v1
	s_lshl_b32 s28, s92, 3
	v_lshl_add_u64 v[68:69], s[4:5], 0, v[60:61]
	v_lshlrev_b32_e32 v60, 2, v14
	v_cmp_lt_i32_e32 vcc, v5, v3
	v_lshl_add_u64 v[70:71], s[4:5], 0, v[60:61]
	s_add_i32 s4, s8, s28
	v_cndmask_b32_e32 v5, v1, v5, vcc
	v_lshlrev_b32_e32 v79, 2, v5
	v_xor_b32_e32 v5, 16, v1
	s_ashr_i32 s5, s4, 31
	s_lshl_b32 s10, s92, 4
	v_cmp_lt_i32_e32 vcc, v5, v3
	s_lshl_b64 s[4:5], s[4:5], 12
	s_add_u32 s4, s76, s4
	v_cndmask_b32_e32 v5, v1, v5, vcc
	v_lshlrev_b32_e32 v80, 2, v5
	v_xor_b32_e32 v5, 32, v1
	s_addc_u32 s5, s77, s5
	s_ashr_i32 s11, s10, 31
	s_ashr_i32 s9, s8, 31
	v_cmp_lt_i32_e32 vcc, v5, v3
	s_lshl_b64 s[12:13], s[10:11], 12
	s_lshl_b64 s[20:21], s[8:9], 12
	v_or_b32_e32 v2, 0x100, v0
	v_or_b32_e32 v4, 0x200, v0
	v_or_b32_e32 v6, 0x300, v0
	v_cndmask_b32_e32 v1, v1, v5, vcc
	s_add_u32 s20, s76, s20
	v_lshlrev_b32_e32 v81, 2, v1
	v_lshlrev_b32_e32 v60, 3, v242
	s_addc_u32 s21, s77, s21
	v_lshlrev_b32_e32 v72, 2, v0
	s_movk_i32 s29, 0x1000
	v_mov_b32_e32 v82, 0x358637bd
	s_mov_b32 s30, 0x800000
	s_mov_b32 s31, 0x7600000
	v_lshlrev_b32_e32 v83, 2, v2
	v_lshlrev_b32_e32 v84, 2, v4
	v_lshlrev_b32_e32 v85, 2, v6
	v_lshlrev_b32_e32 v86, 2, v8
	v_lshlrev_b32_e32 v87, 2, v10
	v_lshlrev_b32_e32 v88, 2, v12
	v_lshlrev_b32_e32 v89, 2, v14
	v_mov_b32_e32 v73, v61
	s_branch .LBB0_116
